# baseline (speedup 1.0000x reference)
.Lctx_strip_47:
	global_load_dwordx4 v[84:87], v[20:21], off offset:-128
	global_load_dwordx4 v[88:91], v[18:19], off offset:-128
	global_load_dwordx4 v[92:95], v[20:21], off offset:-96
	global_load_dwordx4 v[96:99], v[18:19], off offset:-96
	global_load_dwordx4 v[100:103], v[20:21], off offset:-64
	global_load_dwordx4 v[104:107], v[18:19], off offset:-64
	global_load_dwordx4 v[108:111], v[20:21], off offset:-32
	global_load_dwordx4 v[112:115], v[18:19], off offset:-32
	global_load_dwordx4 v[116:119], v[20:21], off
	global_load_dwordx4 v[120:123], v[18:19], off
	global_load_dwordx4 v[124:127], v[20:21], off offset:32
	global_load_dwordx4 v[130:133], v[18:19], off offset:32
	global_load_dwordx4 v[134:137], v[20:21], off offset:64
	global_load_dwordx4 v[138:141], v[18:19], off offset:64
	global_load_dwordx4 v[142:145], v[20:21], off offset:96
	global_load_dwordx4 v[146:149], v[18:19], off offset:96
	s_waitcnt vmcnt(14)
	v_mfma_f32_32x32x16_bf16 v[0:15], v[84:87], v[88:91], v[0:15]
	global_load_dwordx4 v[84:87], v[20:21], off offset:128
	global_load_dwordx4 v[88:91], v[18:19], off offset:128
	s_waitcnt vmcnt(14)
	v_mfma_f32_32x32x16_bf16 v[0:15], v[92:95], v[96:99], v[0:15]
	global_load_dwordx4 v[92:95], v[20:21], off offset:160
	global_load_dwordx4 v[96:99], v[18:19], off offset:160
	s_waitcnt vmcnt(14)
	v_mfma_f32_32x32x16_bf16 v[0:15], v[100:103], v[104:107], v[0:15]
	global_load_dwordx4 v[100:103], v[20:21], off offset:192
	global_load_dwordx4 v[104:107], v[18:19], off offset:192
	s_waitcnt vmcnt(14)
	v_mfma_f32_32x32x16_bf16 v[0:15], v[108:111], v[112:115], v[0:15]
	global_load_dwordx4 v[108:111], v[20:21], off offset:224
	global_load_dwordx4 v[112:115], v[18:19], off offset:224
	s_waitcnt vmcnt(14)
	v_mfma_f32_32x32x16_bf16 v[0:15], v[116:119], v[120:123], v[0:15]
	global_load_dwordx4 v[116:119], v[20:21], off offset:256
	global_load_dwordx4 v[120:123], v[18:19], off offset:256
	s_waitcnt vmcnt(14)
	v_mfma_f32_32x32x16_bf16 v[0:15], v[124:127], v[130:133], v[0:15]
	global_load_dwordx4 v[124:127], v[20:21], off offset:288
	global_load_dwordx4 v[130:133], v[18:19], off offset:288
	s_waitcnt vmcnt(14)
	v_mfma_f32_32x32x16_bf16 v[0:15], v[134:137], v[138:141], v[0:15]
	global_load_dwordx4 v[134:137], v[20:21], off offset:320
	global_load_dwordx4 v[138:141], v[18:19], off offset:320
	s_waitcnt vmcnt(14)
	v_mfma_f32_32x32x16_bf16 v[0:15], v[142:145], v[146:149], v[0:15]
	global_load_dwordx4 v[142:145], v[20:21], off offset:352
	global_load_dwordx4 v[146:149], v[18:19], off offset:352
	s_waitcnt vmcnt(14)
	v_mfma_f32_32x32x16_bf16 v[0:15], v[84:87], v[88:91], v[0:15]
	s_waitcnt vmcnt(12)
	v_mfma_f32_32x32x16_bf16 v[0:15], v[92:95], v[96:99], v[0:15]
	s_waitcnt vmcnt(10)
	v_mfma_f32_32x32x16_bf16 v[0:15], v[100:103], v[104:107], v[0:15]
	s_waitcnt vmcnt(8)
	v_mfma_f32_32x32x16_bf16 v[0:15], v[108:111], v[112:115], v[0:15]
	s_waitcnt vmcnt(6)
	v_mfma_f32_32x32x16_bf16 v[0:15], v[116:119], v[120:123], v[0:15]
	s_waitcnt vmcnt(4)
	v_mfma_f32_32x32x16_bf16 v[0:15], v[124:127], v[130:133], v[0:15]
	s_waitcnt vmcnt(2)
	v_mfma_f32_32x32x16_bf16 v[0:15], v[134:137], v[138:141], v[0:15]
	s_waitcnt vmcnt(0)
	v_mfma_f32_32x32x16_bf16 v[0:15], v[142:145], v[146:149], v[0:15]
	s_nop 0
	v_lshl_add_u64 v[46:47], v[40:41], 0, v[16:17]
	v_mov_b32_e32 v16, 0
	v_lshl_add_u64 v[48:49], v[42:43], 0, v[128:129]
	s_mov_b32 s0, -16
	v_mov_b32_e32 v17, v16
	v_mov_b32_e32 v18, v16
	v_mov_b32_e32 v19, v16
	v_mov_b32_e32 v20, v16
	v_mov_b32_e32 v21, v16
	v_mov_b32_e32 v22, v16
	v_mov_b32_e32 v23, v16
	v_mov_b32_e32 v24, v16
	v_mov_b32_e32 v25, v16
	v_mov_b32_e32 v26, v16
	v_mov_b32_e32 v27, v16
	v_mov_b32_e32 v28, v16
	v_mov_b32_e32 v29, v16
	v_mov_b32_e32 v30, v16
	v_mov_b32_e32 v31, v16
.Lctx_strip_49:
	global_load_dwordx4 v[84:87], v[48:49], off offset:-128
	global_load_dwordx4 v[88:91], v[46:47], off offset:-128
	global_load_dwordx4 v[92:95], v[48:49], off offset:-96
	global_load_dwordx4 v[96:99], v[46:47], off offset:-96
	global_load_dwordx4 v[100:103], v[48:49], off offset:-64
	global_load_dwordx4 v[104:107], v[46:47], off offset:-64
	global_load_dwordx4 v[108:111], v[48:49], off offset:-32
	global_load_dwordx4 v[112:115], v[46:47], off offset:-32
	global_load_dwordx4 v[116:119], v[48:49], off
	global_load_dwordx4 v[120:123], v[46:47], off
	global_load_dwordx4 v[124:127], v[48:49], off offset:32
	global_load_dwordx4 v[130:133], v[46:47], off offset:32
	global_load_dwordx4 v[134:137], v[48:49], off offset:64
	global_load_dwordx4 v[138:141], v[46:47], off offset:64
	global_load_dwordx4 v[142:145], v[48:49], off offset:96
	global_load_dwordx4 v[146:149], v[46:47], off offset:96
	s_waitcnt vmcnt(14)
	v_mfma_f32_32x32x16_bf16 v[16:31], v[84:87], v[88:91], v[16:31]
	global_load_dwordx4 v[84:87], v[48:49], off offset:128
	global_load_dwordx4 v[88:91], v[46:47], off offset:128
	s_waitcnt vmcnt(14)
	v_mfma_f32_32x32x16_bf16 v[16:31], v[92:95], v[96:99], v[16:31]
	global_load_dwordx4 v[92:95], v[48:49], off offset:160
	global_load_dwordx4 v[96:99], v[46:47], off offset:160
	s_waitcnt vmcnt(14)
	v_mfma_f32_32x32x16_bf16 v[16:31], v[100:103], v[104:107], v[16:31]
	global_load_dwordx4 v[100:103], v[48:49], off offset:192
	global_load_dwordx4 v[104:107], v[46:47], off offset:192
	s_waitcnt vmcnt(14)
	v_mfma_f32_32x32x16_bf16 v[16:31], v[108:111], v[112:115], v[16:31]
	global_load_dwordx4 v[108:111], v[48:49], off offset:224
	global_load_dwordx4 v[112:115], v[46:47], off offset:224
	s_waitcnt vmcnt(14)
	v_mfma_f32_32x32x16_bf16 v[16:31], v[116:119], v[120:123], v[16:31]
	global_load_dwordx4 v[116:119], v[48:49], off offset:256
	global_load_dwordx4 v[120:123], v[46:47], off offset:256
	s_waitcnt vmcnt(14)
	v_mfma_f32_32x32x16_bf16 v[16:31], v[124:127], v[130:133], v[16:31]
	global_load_dwordx4 v[124:127], v[48:49], off offset:288
	global_load_dwordx4 v[130:133], v[46:47], off offset:288
	s_waitcnt vmcnt(14)
	v_mfma_f32_32x32x16_bf16 v[16:31], v[134:137], v[138:141], v[16:31]
	global_load_dwordx4 v[134:137], v[48:49], off offset:320
	global_load_dwordx4 v[138:141], v[46:47], off offset:320
	s_waitcnt vmcnt(14)
	v_mfma_f32_32x32x16_bf16 v[16:31], v[142:145], v[146:149], v[16:31]
	global_load_dwordx4 v[142:145], v[48:49], off offset:352
	global_load_dwordx4 v[146:149], v[46:47], off offset:352
	s_waitcnt vmcnt(14)
	v_mfma_f32_32x32x16_bf16 v[16:31], v[84:87], v[88:91], v[16:31]
	s_waitcnt vmcnt(12)
	v_mfma_f32_32x32x16_bf16 v[16:31], v[92:95], v[96:99], v[16:31]
	s_waitcnt vmcnt(10)
	v_mfma_f32_32x32x16_bf16 v[16:31], v[100:103], v[104:107], v[16:31]
	s_waitcnt vmcnt(8)
	v_mfma_f32_32x32x16_bf16 v[16:31], v[108:111], v[112:115], v[16:31]
	s_waitcnt vmcnt(6)
	v_mfma_f32_32x32x16_bf16 v[16:31], v[116:119], v[120:123], v[16:31]
	s_waitcnt vmcnt(4)
	v_mfma_f32_32x32x16_bf16 v[16:31], v[124:127], v[130:133], v[16:31]
	s_waitcnt vmcnt(2)
	v_mfma_f32_32x32x16_bf16 v[16:31], v[134:137], v[138:141], v[16:31]
	s_waitcnt vmcnt(0)
	v_mfma_f32_32x32x16_bf16 v[16:31], v[142:145], v[146:149], v[16:31]
	s_nop 0
	s_and_saveexec_b64 s[0:1], s[4:5]
	s_cbranch_execz .LBB0_52
	ds_write2st64_b32 v50, v0, v1 offset1:1
	s_nop 7
	ds_write2st64_b32 v50, v16, v17 offset0:16 offset1:17
	ds_write2st64_b32 v50, v2, v3 offset0:2 offset1:3
	ds_write2st64_b32 v50, v18, v19 offset0:18 offset1:19
	ds_write2st64_b32 v50, v4, v5 offset0:4 offset1:5
	ds_write2st64_b32 v50, v20, v21 offset0:20 offset1:21
	ds_write2st64_b32 v50, v6, v7 offset0:6 offset1:7
	ds_write2st64_b32 v50, v22, v23 offset0:22 offset1:23
	ds_write2st64_b32 v50, v8, v9 offset0:8 offset1:9
	ds_write2st64_b32 v50, v24, v25 offset0:24 offset1:25
	ds_write2st64_b32 v50, v10, v11 offset0:10 offset1:11
	ds_write2st64_b32 v50, v26, v27 offset0:26 offset1:27
	ds_write2st64_b32 v50, v12, v13 offset0:12 offset1:13
	ds_write2st64_b32 v50, v28, v29 offset0:28 offset1:29
	ds_write2st64_b32 v50, v14, v15 offset0:14 offset1:15
	ds_write2st64_b32 v50, v30, v31 offset0:30 offset1:31

.Lctx_strip_382:
	global_load_dwordx4 v[84:87], v[26:27], off offset:-128
	global_load_dwordx4 v[88:91], v[24:25], off offset:-128
	global_load_dwordx4 v[92:95], v[26:27], off offset:-96
	global_load_dwordx4 v[96:99], v[24:25], off offset:-96
	global_load_dwordx4 v[100:103], v[26:27], off offset:-64
	global_load_dwordx4 v[104:107], v[24:25], off offset:-64
	global_load_dwordx4 v[108:111], v[26:27], off offset:-32
	global_load_dwordx4 v[112:115], v[24:25], off offset:-32
	global_load_dwordx4 v[116:119], v[26:27], off
	global_load_dwordx4 v[120:123], v[24:25], off
	global_load_dwordx4 v[124:127], v[26:27], off offset:32
	global_load_dwordx4 v[130:133], v[24:25], off offset:32
	global_load_dwordx4 v[134:137], v[26:27], off offset:64
	global_load_dwordx4 v[138:141], v[24:25], off offset:64
	global_load_dwordx4 v[142:145], v[26:27], off offset:96
	global_load_dwordx4 v[146:149], v[24:25], off offset:96
	s_waitcnt vmcnt(14)
	v_mfma_f32_32x32x16_bf16 v[0:15], v[84:87], v[88:91], v[0:15]
	global_load_dwordx4 v[84:87], v[26:27], off offset:128
	global_load_dwordx4 v[88:91], v[24:25], off offset:128
	s_waitcnt vmcnt(14)
	v_mfma_f32_32x32x16_bf16 v[0:15], v[92:95], v[96:99], v[0:15]
	global_load_dwordx4 v[92:95], v[26:27], off offset:160
	global_load_dwordx4 v[96:99], v[24:25], off offset:160
	s_waitcnt vmcnt(14)
	v_mfma_f32_32x32x16_bf16 v[0:15], v[100:103], v[104:107], v[0:15]
	global_load_dwordx4 v[100:103], v[26:27], off offset:192
	global_load_dwordx4 v[104:107], v[24:25], off offset:192
	s_waitcnt vmcnt(14)
	v_mfma_f32_32x32x16_bf16 v[0:15], v[108:111], v[112:115], v[0:15]
	global_load_dwordx4 v[108:111], v[26:27], off offset:224
	global_load_dwordx4 v[112:115], v[24:25], off offset:224
	s_waitcnt vmcnt(14)
	v_mfma_f32_32x32x16_bf16 v[0:15], v[116:119], v[120:123], v[0:15]
	global_load_dwordx4 v[116:119], v[26:27], off offset:256
	global_load_dwordx4 v[120:123], v[24:25], off offset:256
	s_waitcnt vmcnt(14)
	v_mfma_f32_32x32x16_bf16 v[0:15], v[124:127], v[130:133], v[0:15]
	global_load_dwordx4 v[124:127], v[26:27], off offset:288
	global_load_dwordx4 v[130:133], v[24:25], off offset:288
	s_waitcnt vmcnt(14)
	v_mfma_f32_32x32x16_bf16 v[0:15], v[134:137], v[138:141], v[0:15]
	global_load_dwordx4 v[134:137], v[26:27], off offset:320
	global_load_dwordx4 v[138:141], v[24:25], off offset:320
	s_waitcnt vmcnt(14)
	v_mfma_f32_32x32x16_bf16 v[0:15], v[142:145], v[146:149], v[0:15]
	global_load_dwordx4 v[142:145], v[26:27], off offset:352
	global_load_dwordx4 v[146:149], v[24:25], off offset:352
	s_waitcnt vmcnt(14)
	v_mfma_f32_32x32x16_bf16 v[0:15], v[84:87], v[88:91], v[0:15]
	global_load_dwordx4 v[84:87], v[26:27], off offset:384
	global_load_dwordx4 v[88:91], v[24:25], off offset:384
	s_waitcnt vmcnt(14)
	v_mfma_f32_32x32x16_bf16 v[0:15], v[92:95], v[96:99], v[0:15]
	global_load_dwordx4 v[92:95], v[26:27], off offset:416
	global_load_dwordx4 v[96:99], v[24:25], off offset:416
	s_waitcnt vmcnt(14)
	v_mfma_f32_32x32x16_bf16 v[0:15], v[100:103], v[104:107], v[0:15]
	global_load_dwordx4 v[100:103], v[26:27], off offset:448
	global_load_dwordx4 v[104:107], v[24:25], off offset:448
	s_waitcnt vmcnt(14)
	v_mfma_f32_32x32x16_bf16 v[0:15], v[108:111], v[112:115], v[0:15]
	global_load_dwordx4 v[108:111], v[26:27], off offset:480
	global_load_dwordx4 v[112:115], v[24:25], off offset:480
	s_waitcnt vmcnt(14)
	v_mfma_f32_32x32x16_bf16 v[0:15], v[116:119], v[120:123], v[0:15]
	global_load_dwordx4 v[116:119], v[26:27], off offset:512
	global_load_dwordx4 v[120:123], v[24:25], off offset:512
	s_waitcnt vmcnt(14)
	v_mfma_f32_32x32x16_bf16 v[0:15], v[124:127], v[130:133], v[0:15]
	global_load_dwordx4 v[124:127], v[26:27], off offset:544
	global_load_dwordx4 v[130:133], v[24:25], off offset:544
	s_waitcnt vmcnt(14)
	v_mfma_f32_32x32x16_bf16 v[0:15], v[134:137], v[138:141], v[0:15]
	global_load_dwordx4 v[134:137], v[26:27], off offset:576
	global_load_dwordx4 v[138:141], v[24:25], off offset:576
	s_waitcnt vmcnt(14)
	v_mfma_f32_32x32x16_bf16 v[0:15], v[142:145], v[146:149], v[0:15]
	global_load_dwordx4 v[142:145], v[26:27], off offset:608
	global_load_dwordx4 v[146:149], v[24:25], off offset:608
	s_waitcnt vmcnt(14)
	v_mfma_f32_32x32x16_bf16 v[0:15], v[84:87], v[88:91], v[0:15]
	global_load_dwordx4 v[84:87], v[26:27], off offset:640
	global_load_dwordx4 v[88:91], v[24:25], off offset:640
	s_waitcnt vmcnt(14)
	v_mfma_f32_32x32x16_bf16 v[0:15], v[92:95], v[96:99], v[0:15]
	global_load_dwordx4 v[92:95], v[26:27], off offset:672
	global_load_dwordx4 v[96:99], v[24:25], off offset:672
	s_waitcnt vmcnt(14)
	v_mfma_f32_32x32x16_bf16 v[0:15], v[100:103], v[104:107], v[0:15]
	global_load_dwordx4 v[100:103], v[26:27], off offset:704
	global_load_dwordx4 v[104:107], v[24:25], off offset:704
	s_waitcnt vmcnt(14)
	v_mfma_f32_32x32x16_bf16 v[0:15], v[108:111], v[112:115], v[0:15]
	global_load_dwordx4 v[108:111], v[26:27], off offset:736
	global_load_dwordx4 v[112:115], v[24:25], off offset:736
	s_waitcnt vmcnt(14)
	v_mfma_f32_32x32x16_bf16 v[0:15], v[116:119], v[120:123], v[0:15]
	global_load_dwordx4 v[116:119], v[26:27], off offset:768
	global_load_dwordx4 v[120:123], v[24:25], off offset:768
	s_waitcnt vmcnt(14)
	v_mfma_f32_32x32x16_bf16 v[0:15], v[124:127], v[130:133], v[0:15]
	global_load_dwordx4 v[124:127], v[26:27], off offset:800
	global_load_dwordx4 v[130:133], v[24:25], off offset:800
	s_waitcnt vmcnt(14)
	v_mfma_f32_32x32x16_bf16 v[0:15], v[134:137], v[138:141], v[0:15]
	global_load_dwordx4 v[134:137], v[26:27], off offset:832
	global_load_dwordx4 v[138:141], v[24:25], off offset:832
	s_waitcnt vmcnt(14)
	v_mfma_f32_32x32x16_bf16 v[0:15], v[142:145], v[146:149], v[0:15]
	global_load_dwordx4 v[142:145], v[26:27], off offset:864
	global_load_dwordx4 v[146:149], v[24:25], off offset:864
	s_waitcnt vmcnt(14)
	v_mfma_f32_32x32x16_bf16 v[0:15], v[84:87], v[88:91], v[0:15]
	s_waitcnt vmcnt(12)
	v_mfma_f32_32x32x16_bf16 v[0:15], v[92:95], v[96:99], v[0:15]
	s_waitcnt vmcnt(10)
	v_mfma_f32_32x32x16_bf16 v[0:15], v[100:103], v[104:107], v[0:15]
	s_waitcnt vmcnt(8)
	v_mfma_f32_32x32x16_bf16 v[0:15], v[108:111], v[112:115], v[0:15]
	s_waitcnt vmcnt(6)
	v_mfma_f32_32x32x16_bf16 v[0:15], v[116:119], v[120:123], v[0:15]
	s_waitcnt vmcnt(4)
	v_mfma_f32_32x32x16_bf16 v[0:15], v[124:127], v[130:133], v[0:15]
	s_waitcnt vmcnt(2)
	v_mfma_f32_32x32x16_bf16 v[0:15], v[134:137], v[138:141], v[0:15]
	s_waitcnt vmcnt(0)
	v_mfma_f32_32x32x16_bf16 v[0:15], v[142:145], v[146:149], v[0:15]
	s_nop 0
	s_and_saveexec_b64 s[0:1], s[6:7]
	s_cbranch_execz .LBB0_385
	s_nop 8
	ds_write2st64_b32 v60, v0, v1 offset1:1
	ds_write2st64_b32 v60, v2, v3 offset0:2 offset1:3
	ds_write2st64_b32 v60, v4, v5 offset0:4 offset1:5
	ds_write2st64_b32 v60, v6, v7 offset0:6 offset1:7
	ds_write2st64_b32 v60, v8, v9 offset0:8 offset1:9
	ds_write2st64_b32 v60, v10, v11 offset0:10 offset1:11
	ds_write2st64_b32 v60, v12, v13 offset0:12 offset1:13
	ds_write2st64_b32 v60, v14, v15 offset0:14 offset1:15
